# v1 stack + MFMA order: each accumulator's two k-steps issued back to back (C forwarded), lower MFMA power
# speedup vs baseline: 1.0122x; 1.0060x over previous
.LBB0_566:
	s_add_u32 s30, s0, 0xfffc0080
	s_addc_u32 s31, s1, -1
	s_add_i32 s52, 0, 0x10000
	s_cmp_eq_u32 s51, 12
	s_cselect_b32 s35, s3, s31
	s_cselect_b32 s34, s25, s30
	s_cselect_b32 s31, s23, s50
	s_cselect_b32 s30, s48, s49
	s_add_i32 s54, 0, 0x14000
	v_add_u32_e32 v158, s52, v199
	v_add_u32_e32 v174, s54, v199
	ds_read_b128 v[134:137], v158
	ds_read_b128 v[150:153], v158 offset:1024
	ds_read_b128 v[154:157], v158 offset:2048
	ds_read_b128 v[158:161], v158 offset:3072
	ds_read_b128 v[162:165], v174
	ds_read_b128 v[166:169], v174 offset:1024
	ds_read_b128 v[170:173], v174 offset:2048
	ds_read_b128 v[182:185], v174 offset:3072
	v_lshl_add_u64 v[174:175], s[0:1], 0, v[146:147]
	s_add_i32 m0, s39, 0xc000
	ds_read_b128 v[186:189], v201
	ds_read_b128 v[202:205], v201 offset:1024
	ds_read_b128 v[206:209], v201 offset:2048
	ds_read_b128 v[210:213], v201 offset:3072
	ds_read_b128 v[214:217], v201 offset:4096
	ds_read_b128 v[218:221], v201 offset:5120
	ds_read_b128 v[222:225], v201 offset:6144
	ds_read_b128 v[226:229], v201 offset:7168
	global_load_lds_dwordx4 v[174:175], off
	v_lshl_add_u64 v[174:175], s[0:1], 0, v[148:149]
	s_add_i32 m0, s39, 0xe000
	s_nop 0
	global_load_lds_dwordx4 v[174:175], off
	s_waitcnt vmcnt(8)
	s_waitcnt lgkmcnt(0)
	s_barrier
	s_setprio 1
	s_waitcnt lgkmcnt(0)
	v_mfma_f32_16x16x32_bf16 v[130:133], v[134:137], v[186:189], v[130:133]
	v_mfma_f32_16x16x32_bf16 v[130:133], v[150:153], v[202:205], v[130:133]
	v_mfma_f32_16x16x32_bf16 v[126:129], v[154:157], v[186:189], v[126:129]
	v_mfma_f32_16x16x32_bf16 v[126:129], v[158:161], v[202:205], v[126:129]
	v_mfma_f32_16x16x32_bf16 v[114:117], v[134:137], v[206:209], v[114:117]
	v_mfma_f32_16x16x32_bf16 v[114:117], v[150:153], v[210:213], v[114:117]
	v_mfma_f32_16x16x32_bf16 v[110:113], v[154:157], v[206:209], v[110:113]
	v_mfma_f32_16x16x32_bf16 v[110:113], v[158:161], v[210:213], v[110:113]
	v_mfma_f32_16x16x32_bf16 v[98:101], v[134:137], v[214:217], v[98:101]
	v_mfma_f32_16x16x32_bf16 v[98:101], v[150:153], v[218:221], v[98:101]
	v_mfma_f32_16x16x32_bf16 v[94:97], v[154:157], v[214:217], v[94:97]
	v_mfma_f32_16x16x32_bf16 v[94:97], v[158:161], v[218:221], v[94:97]
	v_mfma_f32_16x16x32_bf16 v[82:85], v[134:137], v[222:225], v[82:85]
	v_mfma_f32_16x16x32_bf16 v[82:85], v[150:153], v[226:229], v[82:85]
	v_mfma_f32_16x16x32_bf16 v[78:81], v[154:157], v[222:225], v[78:81]
	v_mfma_f32_16x16x32_bf16 v[78:81], v[158:161], v[226:229], v[78:81]
	s_setprio 0
	s_setprio 1
	v_mfma_f32_16x16x32_bf16 v[122:125], v[162:165], v[186:189], v[122:125]
	v_mfma_f32_16x16x32_bf16 v[122:125], v[166:169], v[202:205], v[122:125]
	v_mfma_f32_16x16x32_bf16 v[118:121], v[170:173], v[186:189], v[118:121]
	v_mfma_f32_16x16x32_bf16 v[118:121], v[182:185], v[202:205], v[118:121]
	v_mfma_f32_16x16x32_bf16 v[106:109], v[162:165], v[206:209], v[106:109]
	v_mfma_f32_16x16x32_bf16 v[106:109], v[166:169], v[210:213], v[106:109]
	v_mfma_f32_16x16x32_bf16 v[102:105], v[170:173], v[206:209], v[102:105]
	v_mfma_f32_16x16x32_bf16 v[102:105], v[182:185], v[210:213], v[102:105]
	v_mfma_f32_16x16x32_bf16 v[90:93], v[162:165], v[214:217], v[90:93]
	v_mfma_f32_16x16x32_bf16 v[90:93], v[166:169], v[218:221], v[90:93]
	v_mfma_f32_16x16x32_bf16 v[86:89], v[170:173], v[214:217], v[86:89]
	v_mfma_f32_16x16x32_bf16 v[86:89], v[182:185], v[218:221], v[86:89]
	v_mfma_f32_16x16x32_bf16 v[74:77], v[162:165], v[222:225], v[74:77]
	v_mfma_f32_16x16x32_bf16 v[74:77], v[166:169], v[226:229], v[74:77]
	v_mfma_f32_16x16x32_bf16 v[70:73], v[170:173], v[222:225], v[70:73]
	v_mfma_f32_16x16x32_bf16 v[70:73], v[182:185], v[226:229], v[70:73]
	s_setprio 0
	s_barrier
	s_add_i32 s52, s52, s36
	v_lshl_add_u64 v[174:175], s[30:31], 0, v[0:1]
	s_mov_b32 m0, s52
	ds_read_b128 v[186:189], v201 offset:16384
	ds_read_b128 v[202:205], v201 offset:17408
	ds_read_b128 v[206:209], v201 offset:18432
	ds_read_b128 v[210:213], v201 offset:19456
	ds_read_b128 v[214:217], v201 offset:20480
	ds_read_b128 v[218:221], v201 offset:21504
	ds_read_b128 v[222:225], v201 offset:22528
	ds_read_b128 v[226:229], v201 offset:23552
	global_load_lds_dwordx4 v[174:175], off
	s_add_i32 m0, s52, 0x2000
	s_add_u32 s52, s30, 0x40000
	v_lshl_add_u64 v[190:191], s[30:31], 0, v[14:15]
	s_addc_u32 s53, s31, 0
	s_add_i32 s54, s54, s36
	global_load_lds_dwordx4 v[190:191], off
	v_lshl_add_u64 v[230:231], s[52:53], 0, v[0:1]
	s_mov_b32 m0, s54
	v_lshl_add_u64 v[232:233], s[34:35], 0, v[138:139]
	global_load_lds_dwordx4 v[230:231], off
	v_lshl_add_u64 v[230:231], s[52:53], 0, v[14:15]
	s_add_i32 m0, s54, 0x2000
	s_nop 0
	global_load_lds_dwordx4 v[230:231], off
	v_lshl_add_u64 v[230:231], s[34:35], 0, v[140:141]
	s_mov_b32 m0, s39
	s_nop 0
	global_load_lds_dwordx4 v[230:231], off
	s_mov_b32 m0, s40
	s_nop 0
	global_load_lds_dwordx4 v[232:233], off
	s_waitcnt vmcnt(8)
	s_waitcnt lgkmcnt(0)
	s_barrier
	s_setprio 1
	s_waitcnt lgkmcnt(0)
	v_mfma_f32_16x16x32_bf16 v[66:69], v[134:137], v[186:189], v[66:69]
	v_mfma_f32_16x16x32_bf16 v[66:69], v[150:153], v[202:205], v[66:69]
	v_mfma_f32_16x16x32_bf16 v[62:65], v[154:157], v[186:189], v[62:65]
	v_mfma_f32_16x16x32_bf16 v[62:65], v[158:161], v[202:205], v[62:65]
	v_mfma_f32_16x16x32_bf16 v[50:53], v[134:137], v[206:209], v[50:53]
	v_mfma_f32_16x16x32_bf16 v[50:53], v[150:153], v[210:213], v[50:53]
	v_mfma_f32_16x16x32_bf16 v[46:49], v[154:157], v[206:209], v[46:49]
	v_mfma_f32_16x16x32_bf16 v[46:49], v[158:161], v[210:213], v[46:49]
	v_mfma_f32_16x16x32_bf16 v[34:37], v[134:137], v[214:217], v[34:37]
	v_mfma_f32_16x16x32_bf16 v[34:37], v[150:153], v[218:221], v[34:37]
	v_mfma_f32_16x16x32_bf16 v[30:33], v[154:157], v[214:217], v[30:33]
	v_mfma_f32_16x16x32_bf16 v[30:33], v[158:161], v[218:221], v[30:33]
	v_mfma_f32_16x16x32_bf16 v[18:21], v[134:137], v[222:225], v[18:21]
	v_mfma_f32_16x16x32_bf16 v[18:21], v[150:153], v[226:229], v[18:21]
	v_mfma_f32_16x16x32_bf16 v[10:13], v[154:157], v[222:225], v[10:13]
	v_mfma_f32_16x16x32_bf16 v[10:13], v[158:161], v[226:229], v[10:13]
	s_setprio 0
	s_setprio 1
	v_mfma_f32_16x16x32_bf16 v[58:61], v[162:165], v[186:189], v[58:61]
	v_mfma_f32_16x16x32_bf16 v[58:61], v[166:169], v[202:205], v[58:61]
	v_mfma_f32_16x16x32_bf16 v[54:57], v[170:173], v[186:189], v[54:57]
	v_mfma_f32_16x16x32_bf16 v[54:57], v[182:185], v[202:205], v[54:57]
	v_mfma_f32_16x16x32_bf16 v[42:45], v[162:165], v[206:209], v[42:45]
	v_mfma_f32_16x16x32_bf16 v[42:45], v[166:169], v[210:213], v[42:45]
	v_mfma_f32_16x16x32_bf16 v[38:41], v[170:173], v[206:209], v[38:41]
	v_mfma_f32_16x16x32_bf16 v[38:41], v[182:185], v[210:213], v[38:41]
	v_mfma_f32_16x16x32_bf16 v[26:29], v[162:165], v[214:217], v[26:29]
	v_mfma_f32_16x16x32_bf16 v[26:29], v[166:169], v[218:221], v[26:29]
	v_mfma_f32_16x16x32_bf16 v[22:25], v[170:173], v[214:217], v[22:25]
	v_mfma_f32_16x16x32_bf16 v[22:25], v[182:185], v[218:221], v[22:25]
	v_mfma_f32_16x16x32_bf16 v[6:9], v[162:165], v[222:225], v[6:9]
	v_mfma_f32_16x16x32_bf16 v[6:9], v[166:169], v[226:229], v[6:9]
	v_mfma_f32_16x16x32_bf16 v[2:5], v[170:173], v[222:225], v[2:5]
	v_mfma_f32_16x16x32_bf16 v[2:5], v[182:185], v[226:229], v[2:5]
	s_setprio 0
	s_barrier
	s_add_i32 s52, 0, 0x18000
	s_add_i32 s53, 0, 0x1c000
	v_add_u32_e32 v158, s52, v199
	v_add_u32_e32 v182, s53, v199
	ds_read_b128 v[134:137], v158
	ds_read_b128 v[150:153], v158 offset:1024
	ds_read_b128 v[154:157], v158 offset:2048
	ds_read_b128 v[158:161], v158 offset:3072
	ds_read_b128 v[162:165], v182
	ds_read_b128 v[166:169], v182 offset:1024
	ds_read_b128 v[170:173], v182 offset:2048
	ds_read_b128 v[182:185], v182 offset:3072
	s_add_u32 s34, s34, 0x40000
	s_addc_u32 s35, s35, 0
	s_mov_b32 m0, s41
	v_lshl_add_u64 v[234:235], s[34:35], 0, v[140:141]
	ds_read_b128 v[186:189], v201 offset:32768
	ds_read_b128 v[202:205], v201 offset:33792
	ds_read_b128 v[206:209], v201 offset:34816
	ds_read_b128 v[210:213], v201 offset:35840
	ds_read_b128 v[214:217], v201 offset:36864
	ds_read_b128 v[218:221], v201 offset:37888
	ds_read_b128 v[222:225], v201 offset:38912
	ds_read_b128 v[226:229], v201 offset:39936
	global_load_lds_dwordx4 v[234:235], off
	v_lshl_add_u64 v[234:235], s[34:35], 0, v[138:139]
	s_mov_b32 m0, s42
	s_nop 0
	global_load_lds_dwordx4 v[234:235], off
	s_waitcnt vmcnt(8)
	s_waitcnt lgkmcnt(0)
	s_barrier
	s_setprio 1
	s_waitcnt lgkmcnt(0)
	v_mfma_f32_16x16x32_bf16 v[130:133], v[134:137], v[186:189], v[130:133]
	v_mfma_f32_16x16x32_bf16 v[130:133], v[150:153], v[202:205], v[130:133]
	v_mfma_f32_16x16x32_bf16 v[126:129], v[154:157], v[186:189], v[126:129]
	v_mfma_f32_16x16x32_bf16 v[126:129], v[158:161], v[202:205], v[126:129]
	v_mfma_f32_16x16x32_bf16 v[114:117], v[134:137], v[206:209], v[114:117]
	v_mfma_f32_16x16x32_bf16 v[114:117], v[150:153], v[210:213], v[114:117]
	v_mfma_f32_16x16x32_bf16 v[110:113], v[154:157], v[206:209], v[110:113]
	v_mfma_f32_16x16x32_bf16 v[110:113], v[158:161], v[210:213], v[110:113]
	v_mfma_f32_16x16x32_bf16 v[98:101], v[134:137], v[214:217], v[98:101]
	v_mfma_f32_16x16x32_bf16 v[98:101], v[150:153], v[218:221], v[98:101]
	v_mfma_f32_16x16x32_bf16 v[94:97], v[154:157], v[214:217], v[94:97]
	v_mfma_f32_16x16x32_bf16 v[94:97], v[158:161], v[218:221], v[94:97]
	v_mfma_f32_16x16x32_bf16 v[82:85], v[134:137], v[222:225], v[82:85]
	v_mfma_f32_16x16x32_bf16 v[82:85], v[150:153], v[226:229], v[82:85]
	v_mfma_f32_16x16x32_bf16 v[78:81], v[154:157], v[222:225], v[78:81]
	v_mfma_f32_16x16x32_bf16 v[78:81], v[158:161], v[226:229], v[78:81]
	s_setprio 0
	s_setprio 1
	v_mfma_f32_16x16x32_bf16 v[122:125], v[162:165], v[186:189], v[122:125]
	v_mfma_f32_16x16x32_bf16 v[122:125], v[166:169], v[202:205], v[122:125]
	v_mfma_f32_16x16x32_bf16 v[118:121], v[170:173], v[186:189], v[118:121]
	v_mfma_f32_16x16x32_bf16 v[118:121], v[182:185], v[202:205], v[118:121]
	v_mfma_f32_16x16x32_bf16 v[106:109], v[162:165], v[206:209], v[106:109]
	v_mfma_f32_16x16x32_bf16 v[106:109], v[166:169], v[210:213], v[106:109]
	v_mfma_f32_16x16x32_bf16 v[102:105], v[170:173], v[206:209], v[102:105]
	v_mfma_f32_16x16x32_bf16 v[102:105], v[182:185], v[210:213], v[102:105]
	v_mfma_f32_16x16x32_bf16 v[90:93], v[162:165], v[214:217], v[90:93]
	v_mfma_f32_16x16x32_bf16 v[90:93], v[166:169], v[218:221], v[90:93]
	v_mfma_f32_16x16x32_bf16 v[86:89], v[170:173], v[214:217], v[86:89]
	v_mfma_f32_16x16x32_bf16 v[86:89], v[182:185], v[218:221], v[86:89]
	v_mfma_f32_16x16x32_bf16 v[74:77], v[162:165], v[222:225], v[74:77]
	v_mfma_f32_16x16x32_bf16 v[74:77], v[166:169], v[226:229], v[74:77]
	v_mfma_f32_16x16x32_bf16 v[70:73], v[170:173], v[222:225], v[70:73]
	v_mfma_f32_16x16x32_bf16 v[70:73], v[182:185], v[226:229], v[70:73]
	s_setprio 0
	s_barrier
	s_add_i32 s34, s52, s36
	v_lshl_add_u64 v[174:175], v[174:175], 0, s[92:93]
	s_mov_b32 m0, s34
	ds_read_b128 v[186:189], v201 offset:49152
	ds_read_b128 v[202:205], v201 offset:50176
	ds_read_b128 v[206:209], v201 offset:51200
	ds_read_b128 v[210:213], v201 offset:52224
	ds_read_b128 v[214:217], v201 offset:53248
	ds_read_b128 v[218:221], v201 offset:54272
	ds_read_b128 v[222:225], v201 offset:55296
	ds_read_b128 v[226:229], v201 offset:56320
	global_load_lds_dwordx4 v[174:175], off
	s_add_i32 m0, s34, 0x2000
	s_add_u32 s30, s30, 0x40080
	v_lshl_add_u64 v[174:175], v[190:191], 0, s[92:93]
	s_addc_u32 s31, s31, 0
	s_add_i32 s34, s53, s36
	global_load_lds_dwordx4 v[174:175], off
	v_lshl_add_u64 v[174:175], s[30:31], 0, v[0:1]
	s_mov_b32 m0, s34
	s_nop 0
	global_load_lds_dwordx4 v[174:175], off
	v_lshl_add_u64 v[174:175], s[30:31], 0, v[14:15]
	s_add_i32 m0, s34, 0x2000
	s_nop 0
	global_load_lds_dwordx4 v[174:175], off
	v_lshl_add_u64 v[174:175], v[230:231], 0, s[92:93]
	s_mov_b32 m0, s43
	s_nop 0
	global_load_lds_dwordx4 v[174:175], off
	v_lshl_add_u64 v[174:175], v[232:233], 0, s[92:93]
	s_mov_b32 m0, s44
	s_nop 0
	global_load_lds_dwordx4 v[174:175], off
	s_waitcnt vmcnt(8)
	s_waitcnt lgkmcnt(0)
	s_barrier
	s_setprio 1
	s_waitcnt lgkmcnt(0)
	v_mfma_f32_16x16x32_bf16 v[66:69], v[134:137], v[186:189], v[66:69]
	v_mfma_f32_16x16x32_bf16 v[66:69], v[150:153], v[202:205], v[66:69]
	v_mfma_f32_16x16x32_bf16 v[62:65], v[154:157], v[186:189], v[62:65]
	v_mfma_f32_16x16x32_bf16 v[62:65], v[158:161], v[202:205], v[62:65]
	v_mfma_f32_16x16x32_bf16 v[50:53], v[134:137], v[206:209], v[50:53]
	v_mfma_f32_16x16x32_bf16 v[50:53], v[150:153], v[210:213], v[50:53]
	v_mfma_f32_16x16x32_bf16 v[46:49], v[154:157], v[206:209], v[46:49]
	v_mfma_f32_16x16x32_bf16 v[46:49], v[158:161], v[210:213], v[46:49]
	v_mfma_f32_16x16x32_bf16 v[34:37], v[134:137], v[214:217], v[34:37]
	v_mfma_f32_16x16x32_bf16 v[34:37], v[150:153], v[218:221], v[34:37]
	v_mfma_f32_16x16x32_bf16 v[30:33], v[154:157], v[214:217], v[30:33]
	v_mfma_f32_16x16x32_bf16 v[30:33], v[158:161], v[218:221], v[30:33]
	v_mfma_f32_16x16x32_bf16 v[18:21], v[134:137], v[222:225], v[18:21]
	v_mfma_f32_16x16x32_bf16 v[18:21], v[150:153], v[226:229], v[18:21]
	v_mfma_f32_16x16x32_bf16 v[10:13], v[154:157], v[222:225], v[10:13]
	v_mfma_f32_16x16x32_bf16 v[10:13], v[158:161], v[226:229], v[10:13]
	s_setprio 0
	s_setprio 1
	v_mfma_f32_16x16x32_bf16 v[58:61], v[162:165], v[186:189], v[58:61]
	v_mfma_f32_16x16x32_bf16 v[58:61], v[166:169], v[202:205], v[58:61]
	v_mfma_f32_16x16x32_bf16 v[54:57], v[170:173], v[186:189], v[54:57]
	v_mfma_f32_16x16x32_bf16 v[54:57], v[182:185], v[202:205], v[54:57]
	v_mfma_f32_16x16x32_bf16 v[42:45], v[162:165], v[206:209], v[42:45]
	v_mfma_f32_16x16x32_bf16 v[42:45], v[166:169], v[210:213], v[42:45]
	v_mfma_f32_16x16x32_bf16 v[38:41], v[170:173], v[206:209], v[38:41]
	v_mfma_f32_16x16x32_bf16 v[38:41], v[182:185], v[210:213], v[38:41]
	v_mfma_f32_16x16x32_bf16 v[26:29], v[162:165], v[214:217], v[26:29]
	v_mfma_f32_16x16x32_bf16 v[26:29], v[166:169], v[218:221], v[26:29]
	v_mfma_f32_16x16x32_bf16 v[22:25], v[170:173], v[214:217], v[22:25]
	v_mfma_f32_16x16x32_bf16 v[22:25], v[182:185], v[218:221], v[22:25]
	v_mfma_f32_16x16x32_bf16 v[6:9], v[162:165], v[222:225], v[6:9]
	v_mfma_f32_16x16x32_bf16 v[6:9], v[166:169], v[226:229], v[6:9]
	v_mfma_f32_16x16x32_bf16 v[2:5], v[170:173], v[222:225], v[2:5]
	v_mfma_f32_16x16x32_bf16 v[2:5], v[182:185], v[226:229], v[2:5]
	s_setprio 0
	s_barrier
	s_add_i32 s51, s51, 2
	s_add_u32 s0, s0, 0x100
	s_addc_u32 s1, s1, 0
	s_add_u32 s49, s49, 0x100
	s_addc_u32 s50, s50, 0
	s_cmp_gt_u32 s51, 13
	s_cbranch_scc0 .LBB0_566
	s_and_b64 vcc, exec, s[18:19]
	s_cbranch_vccz .LBB0_569
	s_barrier

.LBB0_637:
	s_add_i32 s47, s24, 2
	s_add_u32 s48, s22, 0x80
	s_addc_u32 s25, s23, 0
	s_add_i32 s50, 0, 0x10000
	s_cmp_eq_u32 s40, s24
	s_cselect_b32 s25, s7, s25
	s_cselect_b32 s24, s6, s48
	v_add_u32_e32 v135, s50, v249
	s_cselect_b32 s49, s21, s46
	s_cselect_b32 s48, s20, s45
	s_add_i32 s51, 0, 0x14000
	ds_read_b128 v[142:145], v135
	ds_read_b128 v[146:149], v135 offset:1024
	ds_read_b128 v[150:153], v135 offset:2048
	ds_read_b128 v[154:157], v135 offset:3072
	v_add_u32_e32 v135, s51, v249
	ds_read_b128 v[158:161], v135
	ds_read_b128 v[162:165], v135 offset:1024
	ds_read_b128 v[166:169], v135 offset:2048
	ds_read_b128 v[170:173], v135 offset:3072
	v_lshl_add_u64 v[174:175], s[22:23], 0, v[138:139]
	s_add_i32 m0, s31, 0xc000
	ds_read_b128 v[182:185], v251
	ds_read_b128 v[186:189], v251 offset:1024
	ds_read_b128 v[190:193], v251 offset:2048
	ds_read_b128 v[194:197], v251 offset:3072
	ds_read_b128 v[198:201], v251 offset:4096
	ds_read_b128 v[202:205], v251 offset:5120
	ds_read_b128 v[206:209], v251 offset:6144
	ds_read_b128 v[210:213], v251 offset:7168
	global_load_lds_dwordx4 v[174:175], off
	v_lshl_add_u64 v[174:175], s[22:23], 0, v[140:141]
	s_add_i32 m0, s31, 0xe000
	s_nop 0
	global_load_lds_dwordx4 v[174:175], off
	s_waitcnt vmcnt(8)
	s_waitcnt lgkmcnt(0)
	s_barrier
	s_setprio 1
	s_waitcnt lgkmcnt(0)
	v_mfma_f32_16x16x32_bf16 v[130:133], v[142:145], v[182:185], v[130:133]
	v_mfma_f32_16x16x32_bf16 v[130:133], v[146:149], v[186:189], v[130:133]
	v_mfma_f32_16x16x32_bf16 v[126:129], v[150:153], v[182:185], v[126:129]
	v_mfma_f32_16x16x32_bf16 v[126:129], v[154:157], v[186:189], v[126:129]
	v_mfma_f32_16x16x32_bf16 v[114:117], v[142:145], v[190:193], v[114:117]
	v_mfma_f32_16x16x32_bf16 v[114:117], v[146:149], v[194:197], v[114:117]
	v_mfma_f32_16x16x32_bf16 v[110:113], v[150:153], v[190:193], v[110:113]
	v_mfma_f32_16x16x32_bf16 v[110:113], v[154:157], v[194:197], v[110:113]
	v_mfma_f32_16x16x32_bf16 v[98:101], v[142:145], v[198:201], v[98:101]
	v_mfma_f32_16x16x32_bf16 v[98:101], v[146:149], v[202:205], v[98:101]
	v_mfma_f32_16x16x32_bf16 v[94:97], v[150:153], v[198:201], v[94:97]
	v_mfma_f32_16x16x32_bf16 v[94:97], v[154:157], v[202:205], v[94:97]
	v_mfma_f32_16x16x32_bf16 v[82:85], v[142:145], v[206:209], v[82:85]
	v_mfma_f32_16x16x32_bf16 v[82:85], v[146:149], v[210:213], v[82:85]
	v_mfma_f32_16x16x32_bf16 v[78:81], v[150:153], v[206:209], v[78:81]
	v_mfma_f32_16x16x32_bf16 v[78:81], v[154:157], v[210:213], v[78:81]
	s_setprio 0
	s_setprio 1
	v_mfma_f32_16x16x32_bf16 v[122:125], v[158:161], v[182:185], v[122:125]
	v_mfma_f32_16x16x32_bf16 v[122:125], v[162:165], v[186:189], v[122:125]
	v_mfma_f32_16x16x32_bf16 v[118:121], v[166:169], v[182:185], v[118:121]
	v_mfma_f32_16x16x32_bf16 v[118:121], v[170:173], v[186:189], v[118:121]
	v_mfma_f32_16x16x32_bf16 v[106:109], v[158:161], v[190:193], v[106:109]
	v_mfma_f32_16x16x32_bf16 v[106:109], v[162:165], v[194:197], v[106:109]
	v_mfma_f32_16x16x32_bf16 v[102:105], v[166:169], v[190:193], v[102:105]
	v_mfma_f32_16x16x32_bf16 v[102:105], v[170:173], v[194:197], v[102:105]
	v_mfma_f32_16x16x32_bf16 v[90:93], v[158:161], v[198:201], v[90:93]
	v_mfma_f32_16x16x32_bf16 v[90:93], v[162:165], v[202:205], v[90:93]
	v_mfma_f32_16x16x32_bf16 v[86:89], v[166:169], v[198:201], v[86:89]
	v_mfma_f32_16x16x32_bf16 v[86:89], v[170:173], v[202:205], v[86:89]
	v_mfma_f32_16x16x32_bf16 v[74:77], v[158:161], v[206:209], v[74:77]
	v_mfma_f32_16x16x32_bf16 v[74:77], v[162:165], v[210:213], v[74:77]
	v_mfma_f32_16x16x32_bf16 v[70:73], v[166:169], v[206:209], v[70:73]
	v_mfma_f32_16x16x32_bf16 v[70:73], v[170:173], v[210:213], v[70:73]
	s_setprio 0
	s_barrier
	s_add_i32 s50, s50, s30
	v_lshl_add_u64 v[174:175], s[48:49], 0, v[0:1]
	s_mov_b32 m0, s50
	ds_read_b128 v[182:185], v251 offset:16384
	ds_read_b128 v[186:189], v251 offset:17408
	ds_read_b128 v[190:193], v251 offset:18432
	ds_read_b128 v[194:197], v251 offset:19456
	ds_read_b128 v[198:201], v251 offset:20480
	ds_read_b128 v[202:205], v251 offset:21504
	ds_read_b128 v[206:209], v251 offset:22528
	ds_read_b128 v[210:213], v251 offset:23552
	global_load_lds_dwordx4 v[174:175], off
	s_add_i32 m0, s50, 0x2000
	v_lshl_add_u64 v[214:215], s[48:49], 0, v[14:15]
	s_add_u32 s48, s48, s10
	s_addc_u32 s49, s49, 0
	s_add_i32 s50, s51, s30
	global_load_lds_dwordx4 v[214:215], off
	v_lshl_add_u64 v[216:217], s[48:49], 0, v[0:1]
	s_mov_b32 m0, s50
	v_lshl_add_u64 v[218:219], s[48:49], 0, v[14:15]
	global_load_lds_dwordx4 v[216:217], off
	s_add_i32 m0, s50, 0x2000
	v_lshl_add_u64 v[220:221], s[24:25], 0, v[0:1]
	global_load_lds_dwordx4 v[218:219], off
	s_mov_b32 m0, s31
	v_lshl_add_u64 v[222:223], s[24:25], 0, v[14:15]
	global_load_lds_dwordx4 v[220:221], off
	s_mov_b32 m0, s34
	s_nop 0
	global_load_lds_dwordx4 v[222:223], off
	s_waitcnt vmcnt(8)
	s_waitcnt lgkmcnt(0)
	s_barrier
	s_setprio 1
	s_waitcnt lgkmcnt(0)
	v_mfma_f32_16x16x32_bf16 v[66:69], v[142:145], v[182:185], v[66:69]
	v_mfma_f32_16x16x32_bf16 v[66:69], v[146:149], v[186:189], v[66:69]
	v_mfma_f32_16x16x32_bf16 v[62:65], v[150:153], v[182:185], v[62:65]
	v_mfma_f32_16x16x32_bf16 v[62:65], v[154:157], v[186:189], v[62:65]
	v_mfma_f32_16x16x32_bf16 v[50:53], v[142:145], v[190:193], v[50:53]
	v_mfma_f32_16x16x32_bf16 v[50:53], v[146:149], v[194:197], v[50:53]
	v_mfma_f32_16x16x32_bf16 v[46:49], v[150:153], v[190:193], v[46:49]
	v_mfma_f32_16x16x32_bf16 v[46:49], v[154:157], v[194:197], v[46:49]
	v_mfma_f32_16x16x32_bf16 v[34:37], v[142:145], v[198:201], v[34:37]
	v_mfma_f32_16x16x32_bf16 v[34:37], v[146:149], v[202:205], v[34:37]
	v_mfma_f32_16x16x32_bf16 v[30:33], v[150:153], v[198:201], v[30:33]
	v_mfma_f32_16x16x32_bf16 v[30:33], v[154:157], v[202:205], v[30:33]
	v_mfma_f32_16x16x32_bf16 v[18:21], v[142:145], v[206:209], v[18:21]
	v_mfma_f32_16x16x32_bf16 v[18:21], v[146:149], v[210:213], v[18:21]
	v_mfma_f32_16x16x32_bf16 v[10:13], v[150:153], v[206:209], v[10:13]
	v_mfma_f32_16x16x32_bf16 v[10:13], v[154:157], v[210:213], v[10:13]
	s_setprio 0
	s_setprio 1
	v_mfma_f32_16x16x32_bf16 v[58:61], v[158:161], v[182:185], v[58:61]
	v_mfma_f32_16x16x32_bf16 v[58:61], v[162:165], v[186:189], v[58:61]
	v_mfma_f32_16x16x32_bf16 v[54:57], v[166:169], v[182:185], v[54:57]
	v_mfma_f32_16x16x32_bf16 v[54:57], v[170:173], v[186:189], v[54:57]
	v_mfma_f32_16x16x32_bf16 v[42:45], v[158:161], v[190:193], v[42:45]
	v_mfma_f32_16x16x32_bf16 v[42:45], v[162:165], v[194:197], v[42:45]
	v_mfma_f32_16x16x32_bf16 v[38:41], v[166:169], v[190:193], v[38:41]
	v_mfma_f32_16x16x32_bf16 v[38:41], v[170:173], v[194:197], v[38:41]
	v_mfma_f32_16x16x32_bf16 v[26:29], v[158:161], v[198:201], v[26:29]
	v_mfma_f32_16x16x32_bf16 v[26:29], v[162:165], v[202:205], v[26:29]
	v_mfma_f32_16x16x32_bf16 v[22:25], v[166:169], v[198:201], v[22:25]
	v_mfma_f32_16x16x32_bf16 v[22:25], v[170:173], v[202:205], v[22:25]
	v_mfma_f32_16x16x32_bf16 v[6:9], v[158:161], v[206:209], v[6:9]
	v_mfma_f32_16x16x32_bf16 v[6:9], v[162:165], v[210:213], v[6:9]
	v_mfma_f32_16x16x32_bf16 v[2:5], v[166:169], v[206:209], v[2:5]
	v_mfma_f32_16x16x32_bf16 v[2:5], v[170:173], v[210:213], v[2:5]
	s_setprio 0
	s_barrier
	s_add_i32 s48, 0, 0x18000
	v_add_u32_e32 v135, s48, v249
	s_add_i32 s49, 0, 0x1c000
	ds_read_b128 v[142:145], v135
	ds_read_b128 v[146:149], v135 offset:1024
	ds_read_b128 v[150:153], v135 offset:2048
	ds_read_b128 v[154:157], v135 offset:3072
	v_add_u32_e32 v135, s49, v249
	ds_read_b128 v[158:161], v135
	ds_read_b128 v[162:165], v135 offset:1024
	ds_read_b128 v[166:169], v135 offset:2048
	ds_read_b128 v[170:173], v135 offset:3072
	s_add_u32 s24, s24, s10
	s_addc_u32 s25, s25, 0
	s_mov_b32 m0, s35
	v_lshl_add_u64 v[224:225], s[24:25], 0, v[0:1]
	ds_read_b128 v[182:185], v251 offset:32768
	ds_read_b128 v[186:189], v251 offset:33792
	ds_read_b128 v[190:193], v251 offset:34816
	ds_read_b128 v[194:197], v251 offset:35840
	ds_read_b128 v[198:201], v251 offset:36864
	ds_read_b128 v[202:205], v251 offset:37888
	ds_read_b128 v[206:209], v251 offset:38912
	ds_read_b128 v[210:213], v251 offset:39936
	global_load_lds_dwordx4 v[224:225], off
	v_lshl_add_u64 v[224:225], s[24:25], 0, v[14:15]
	s_mov_b32 m0, s36
	s_nop 0
	global_load_lds_dwordx4 v[224:225], off
	s_waitcnt vmcnt(8)
	s_waitcnt lgkmcnt(0)
	s_barrier
	s_setprio 1
	s_waitcnt lgkmcnt(0)
	v_mfma_f32_16x16x32_bf16 v[130:133], v[142:145], v[182:185], v[130:133]
	v_mfma_f32_16x16x32_bf16 v[130:133], v[146:149], v[186:189], v[130:133]
	v_mfma_f32_16x16x32_bf16 v[126:129], v[150:153], v[182:185], v[126:129]
	v_mfma_f32_16x16x32_bf16 v[126:129], v[154:157], v[186:189], v[126:129]
	v_mfma_f32_16x16x32_bf16 v[114:117], v[142:145], v[190:193], v[114:117]
	v_mfma_f32_16x16x32_bf16 v[114:117], v[146:149], v[194:197], v[114:117]
	v_mfma_f32_16x16x32_bf16 v[110:113], v[150:153], v[190:193], v[110:113]
	v_mfma_f32_16x16x32_bf16 v[110:113], v[154:157], v[194:197], v[110:113]
	v_mfma_f32_16x16x32_bf16 v[98:101], v[142:145], v[198:201], v[98:101]
	v_mfma_f32_16x16x32_bf16 v[98:101], v[146:149], v[202:205], v[98:101]
	v_mfma_f32_16x16x32_bf16 v[94:97], v[150:153], v[198:201], v[94:97]
	v_mfma_f32_16x16x32_bf16 v[94:97], v[154:157], v[202:205], v[94:97]
	v_mfma_f32_16x16x32_bf16 v[82:85], v[142:145], v[206:209], v[82:85]
	v_mfma_f32_16x16x32_bf16 v[82:85], v[146:149], v[210:213], v[82:85]
	v_mfma_f32_16x16x32_bf16 v[78:81], v[150:153], v[206:209], v[78:81]
	v_mfma_f32_16x16x32_bf16 v[78:81], v[154:157], v[210:213], v[78:81]
	s_setprio 0
	s_setprio 1
	v_mfma_f32_16x16x32_bf16 v[122:125], v[158:161], v[182:185], v[122:125]
	v_mfma_f32_16x16x32_bf16 v[122:125], v[162:165], v[186:189], v[122:125]
	v_mfma_f32_16x16x32_bf16 v[118:121], v[166:169], v[182:185], v[118:121]
	v_mfma_f32_16x16x32_bf16 v[118:121], v[170:173], v[186:189], v[118:121]
	v_mfma_f32_16x16x32_bf16 v[106:109], v[158:161], v[190:193], v[106:109]
	v_mfma_f32_16x16x32_bf16 v[106:109], v[162:165], v[194:197], v[106:109]
	v_mfma_f32_16x16x32_bf16 v[102:105], v[166:169], v[190:193], v[102:105]
	v_mfma_f32_16x16x32_bf16 v[102:105], v[170:173], v[194:197], v[102:105]
	v_mfma_f32_16x16x32_bf16 v[90:93], v[158:161], v[198:201], v[90:93]
	v_mfma_f32_16x16x32_bf16 v[90:93], v[162:165], v[202:205], v[90:93]
	v_mfma_f32_16x16x32_bf16 v[86:89], v[166:169], v[198:201], v[86:89]
	v_mfma_f32_16x16x32_bf16 v[86:89], v[170:173], v[202:205], v[86:89]
	v_mfma_f32_16x16x32_bf16 v[74:77], v[158:161], v[206:209], v[74:77]
	v_mfma_f32_16x16x32_bf16 v[74:77], v[162:165], v[210:213], v[74:77]
	v_mfma_f32_16x16x32_bf16 v[70:73], v[166:169], v[206:209], v[70:73]
	v_mfma_f32_16x16x32_bf16 v[70:73], v[170:173], v[210:213], v[70:73]
	s_setprio 0
	s_barrier
	s_add_i32 s24, s48, s30
	v_lshl_add_u64 v[174:175], v[174:175], 0, s[92:93]
	s_mov_b32 m0, s24
	ds_read_b128 v[182:185], v251 offset:49152
	ds_read_b128 v[186:189], v251 offset:50176
	ds_read_b128 v[190:193], v251 offset:51200
	ds_read_b128 v[194:197], v251 offset:52224
	ds_read_b128 v[198:201], v251 offset:53248
	ds_read_b128 v[202:205], v251 offset:54272
	ds_read_b128 v[206:209], v251 offset:55296
	ds_read_b128 v[210:213], v251 offset:56320
	global_load_lds_dwordx4 v[174:175], off
	v_lshl_add_u64 v[174:175], v[214:215], 0, s[92:93]
	s_add_i32 m0, s24, 0x2000
	s_add_i32 s24, s49, s30
	global_load_lds_dwordx4 v[174:175], off
	v_lshl_add_u64 v[174:175], v[216:217], 0, s[92:93]
	s_mov_b32 m0, s24
	s_nop 0
	global_load_lds_dwordx4 v[174:175], off
	v_lshl_add_u64 v[174:175], v[218:219], 0, s[92:93]
	s_add_i32 m0, s24, 0x2000
	s_nop 0
	global_load_lds_dwordx4 v[174:175], off
	v_lshl_add_u64 v[174:175], v[220:221], 0, s[92:93]
	s_mov_b32 m0, s37
	s_nop 0
	global_load_lds_dwordx4 v[174:175], off
	v_lshl_add_u64 v[174:175], v[222:223], 0, s[92:93]
	s_mov_b32 m0, s38
	s_nop 0
	global_load_lds_dwordx4 v[174:175], off
	s_waitcnt vmcnt(8)
	s_waitcnt lgkmcnt(0)
	s_barrier
	s_setprio 1
	s_waitcnt lgkmcnt(0)
	v_mfma_f32_16x16x32_bf16 v[66:69], v[142:145], v[182:185], v[66:69]
	v_mfma_f32_16x16x32_bf16 v[66:69], v[146:149], v[186:189], v[66:69]
	v_mfma_f32_16x16x32_bf16 v[62:65], v[150:153], v[182:185], v[62:65]
	v_mfma_f32_16x16x32_bf16 v[62:65], v[154:157], v[186:189], v[62:65]
	v_mfma_f32_16x16x32_bf16 v[50:53], v[142:145], v[190:193], v[50:53]
	v_mfma_f32_16x16x32_bf16 v[50:53], v[146:149], v[194:197], v[50:53]
	v_mfma_f32_16x16x32_bf16 v[46:49], v[150:153], v[190:193], v[46:49]
	v_mfma_f32_16x16x32_bf16 v[46:49], v[154:157], v[194:197], v[46:49]
	v_mfma_f32_16x16x32_bf16 v[34:37], v[142:145], v[198:201], v[34:37]
	v_mfma_f32_16x16x32_bf16 v[34:37], v[146:149], v[202:205], v[34:37]
	v_mfma_f32_16x16x32_bf16 v[30:33], v[150:153], v[198:201], v[30:33]
	v_mfma_f32_16x16x32_bf16 v[30:33], v[154:157], v[202:205], v[30:33]
	v_mfma_f32_16x16x32_bf16 v[18:21], v[142:145], v[206:209], v[18:21]
	v_mfma_f32_16x16x32_bf16 v[18:21], v[146:149], v[210:213], v[18:21]
	v_mfma_f32_16x16x32_bf16 v[10:13], v[150:153], v[206:209], v[10:13]
	v_mfma_f32_16x16x32_bf16 v[10:13], v[154:157], v[210:213], v[10:13]
	s_setprio 0
	s_setprio 1
	v_mfma_f32_16x16x32_bf16 v[58:61], v[158:161], v[182:185], v[58:61]
	v_mfma_f32_16x16x32_bf16 v[58:61], v[162:165], v[186:189], v[58:61]
	v_mfma_f32_16x16x32_bf16 v[54:57], v[166:169], v[182:185], v[54:57]
	v_mfma_f32_16x16x32_bf16 v[54:57], v[170:173], v[186:189], v[54:57]
	v_mfma_f32_16x16x32_bf16 v[42:45], v[158:161], v[190:193], v[42:45]
	v_mfma_f32_16x16x32_bf16 v[42:45], v[162:165], v[194:197], v[42:45]
	v_mfma_f32_16x16x32_bf16 v[38:41], v[166:169], v[190:193], v[38:41]
	v_mfma_f32_16x16x32_bf16 v[38:41], v[170:173], v[194:197], v[38:41]
	v_mfma_f32_16x16x32_bf16 v[26:29], v[158:161], v[198:201], v[26:29]
	v_mfma_f32_16x16x32_bf16 v[26:29], v[162:165], v[202:205], v[26:29]
	v_mfma_f32_16x16x32_bf16 v[22:25], v[166:169], v[198:201], v[22:25]
	v_mfma_f32_16x16x32_bf16 v[22:25], v[170:173], v[202:205], v[22:25]
	v_mfma_f32_16x16x32_bf16 v[6:9], v[158:161], v[206:209], v[6:9]
	v_mfma_f32_16x16x32_bf16 v[6:9], v[162:165], v[210:213], v[6:9]
	v_mfma_f32_16x16x32_bf16 v[2:5], v[166:169], v[206:209], v[2:5]
	v_mfma_f32_16x16x32_bf16 v[2:5], v[170:173], v[210:213], v[2:5]
	s_setprio 0
	s_barrier
	s_add_u32 s22, s22, 0x100
	s_addc_u32 s23, s23, 0
	s_add_u32 s45, s45, 0x100
	s_addc_u32 s46, s46, 0
	s_cmp_ge_u32 s47, s39
	s_mov_b32 s24, s47
	s_cbranch_scc0 .LBB0_637
	s_and_b64 vcc, exec, s[18:19]
	s_cbranch_vccz .LBB0_640
	s_barrier

.Lg3_join_w1:
	s_waitcnt lgkmcnt(0)
	s_barrier
	s_setprio 1
	s_waitcnt lgkmcnt(0)
	v_mfma_f32_16x16x32_bf16 v[130:133], v[134:137], v[194:197], v[130:133]
	v_mfma_f32_16x16x32_bf16 v[130:133], v[148:151], v[198:201], v[130:133]
	v_mfma_f32_16x16x32_bf16 v[122:125], v[152:155], v[194:197], v[122:125]
	v_mfma_f32_16x16x32_bf16 v[122:125], v[156:159], v[198:201], v[122:125]
	v_mfma_f32_16x16x32_bf16 v[114:117], v[134:137], v[202:205], v[114:117]
	v_mfma_f32_16x16x32_bf16 v[114:117], v[148:151], v[206:209], v[114:117]
	v_mfma_f32_16x16x32_bf16 v[106:109], v[152:155], v[202:205], v[106:109]
	v_mfma_f32_16x16x32_bf16 v[106:109], v[156:159], v[206:209], v[106:109]
	v_mfma_f32_16x16x32_bf16 v[98:101], v[134:137], v[210:213], v[98:101]
	v_mfma_f32_16x16x32_bf16 v[98:101], v[148:151], v[214:217], v[98:101]
	v_mfma_f32_16x16x32_bf16 v[90:93], v[152:155], v[210:213], v[90:93]
	v_mfma_f32_16x16x32_bf16 v[90:93], v[156:159], v[214:217], v[90:93]
	v_mfma_f32_16x16x32_bf16 v[82:85], v[134:137], v[218:221], v[82:85]
	v_mfma_f32_16x16x32_bf16 v[82:85], v[148:151], v[222:225], v[82:85]
	v_mfma_f32_16x16x32_bf16 v[74:77], v[152:155], v[218:221], v[74:77]
	v_mfma_f32_16x16x32_bf16 v[74:77], v[156:159], v[222:225], v[74:77]
	s_setprio 0
	s_setprio 1
	v_mfma_f32_16x16x32_bf16 v[126:129], v[160:163], v[194:197], v[126:129]
	v_mfma_f32_16x16x32_bf16 v[126:129], v[182:185], v[198:201], v[126:129]
	v_mfma_f32_16x16x32_bf16 v[118:121], v[186:189], v[194:197], v[118:121]
	v_mfma_f32_16x16x32_bf16 v[118:121], v[190:193], v[198:201], v[118:121]
	v_mfma_f32_16x16x32_bf16 v[110:113], v[160:163], v[202:205], v[110:113]
	v_mfma_f32_16x16x32_bf16 v[110:113], v[182:185], v[206:209], v[110:113]
	v_mfma_f32_16x16x32_bf16 v[102:105], v[186:189], v[202:205], v[102:105]
	v_mfma_f32_16x16x32_bf16 v[102:105], v[190:193], v[206:209], v[102:105]
	v_mfma_f32_16x16x32_bf16 v[94:97], v[160:163], v[210:213], v[94:97]
	v_mfma_f32_16x16x32_bf16 v[94:97], v[182:185], v[214:217], v[94:97]
	v_mfma_f32_16x16x32_bf16 v[86:89], v[186:189], v[210:213], v[86:89]
	v_mfma_f32_16x16x32_bf16 v[86:89], v[190:193], v[214:217], v[86:89]
	v_mfma_f32_16x16x32_bf16 v[78:81], v[160:163], v[218:221], v[78:81]
	v_mfma_f32_16x16x32_bf16 v[78:81], v[182:185], v[222:225], v[78:81]
	v_mfma_f32_16x16x32_bf16 v[70:73], v[186:189], v[218:221], v[70:73]
	v_mfma_f32_16x16x32_bf16 v[70:73], v[190:193], v[222:225], v[70:73]
	s_setprio 0
	s_barrier
	s_add_i32 s41, s41, s13
	v_lshl_add_u64 v[226:227], s[20:21], 0, v[0:1]
	s_mov_b32 m0, s41
	ds_read_b128 v[194:197], v175 offset:16384
	ds_read_b128 v[198:201], v175 offset:17408
	ds_read_b128 v[202:205], v175 offset:18432
	ds_read_b128 v[206:209], v175 offset:19456
	ds_read_b128 v[210:213], v175 offset:20480
	ds_read_b128 v[214:217], v175 offset:21504
	ds_read_b128 v[218:221], v175 offset:22528
	ds_read_b128 v[222:225], v175 offset:23552
	global_load_lds_dwordx4 v[226:227], off
	s_add_i32 m0, s41, 0x2000
	s_add_u32 s42, s20, 0x40000
	v_lshl_add_u64 v[228:229], s[20:21], 0, v[14:15]
	s_addc_u32 s43, s21, 0
	s_add_i32 s41, s44, s13
	global_load_lds_dwordx4 v[228:229], off
	v_lshl_add_u64 v[230:231], s[42:43], 0, v[0:1]
	s_mov_b32 m0, s41
	v_lshl_add_u64 v[232:233], s[22:23], 0, v[138:139]
	global_load_lds_dwordx4 v[230:231], off
	v_lshl_add_u64 v[230:231], s[42:43], 0, v[14:15]
	s_add_i32 m0, s41, 0x2000
	s_nop 0
	global_load_lds_dwordx4 v[230:231], off
	v_lshl_add_u64 v[230:231], s[22:23], 0, v[140:141]
	s_mov_b32 m0, s26
	s_nop 0
	global_load_lds_dwordx4 v[230:231], off
	s_mov_b32 m0, s27
	s_nop 0
	global_load_lds_dwordx4 v[232:233], off
	s_cmp_eq_i32 s40, -2
	s_cselect_b32 s98, s2, 0
	s_cmp_lg_u32 s98, 0
	s_cbranch_scc1 .Lg3_relax_w2
	s_waitcnt vmcnt(8)
	s_branch .Lg3_join_w2

.Lg3_join_w2:
	s_waitcnt lgkmcnt(0)
	s_barrier
	s_setprio 1
	s_waitcnt lgkmcnt(0)
	v_mfma_f32_16x16x32_bf16 v[66:69], v[134:137], v[194:197], v[66:69]
	v_mfma_f32_16x16x32_bf16 v[66:69], v[148:151], v[198:201], v[66:69]
	v_mfma_f32_16x16x32_bf16 v[58:61], v[152:155], v[194:197], v[58:61]
	v_mfma_f32_16x16x32_bf16 v[58:61], v[156:159], v[198:201], v[58:61]
	v_mfma_f32_16x16x32_bf16 v[50:53], v[134:137], v[202:205], v[50:53]
	v_mfma_f32_16x16x32_bf16 v[50:53], v[148:151], v[206:209], v[50:53]
	v_mfma_f32_16x16x32_bf16 v[42:45], v[152:155], v[202:205], v[42:45]
	v_mfma_f32_16x16x32_bf16 v[42:45], v[156:159], v[206:209], v[42:45]
	v_mfma_f32_16x16x32_bf16 v[34:37], v[134:137], v[210:213], v[34:37]
	v_mfma_f32_16x16x32_bf16 v[34:37], v[148:151], v[214:217], v[34:37]
	v_mfma_f32_16x16x32_bf16 v[26:29], v[152:155], v[210:213], v[26:29]
	v_mfma_f32_16x16x32_bf16 v[26:29], v[156:159], v[214:217], v[26:29]
	v_mfma_f32_16x16x32_bf16 v[18:21], v[134:137], v[218:221], v[18:21]
	v_mfma_f32_16x16x32_bf16 v[18:21], v[148:151], v[222:225], v[18:21]
	v_mfma_f32_16x16x32_bf16 v[6:9], v[152:155], v[218:221], v[6:9]
	v_mfma_f32_16x16x32_bf16 v[6:9], v[156:159], v[222:225], v[6:9]
	s_setprio 0
	s_setprio 1
	v_mfma_f32_16x16x32_bf16 v[62:65], v[160:163], v[194:197], v[62:65]
	v_mfma_f32_16x16x32_bf16 v[62:65], v[182:185], v[198:201], v[62:65]
	v_mfma_f32_16x16x32_bf16 v[54:57], v[186:189], v[194:197], v[54:57]
	v_mfma_f32_16x16x32_bf16 v[54:57], v[190:193], v[198:201], v[54:57]
	v_mfma_f32_16x16x32_bf16 v[46:49], v[160:163], v[202:205], v[46:49]
	v_mfma_f32_16x16x32_bf16 v[46:49], v[182:185], v[206:209], v[46:49]
	v_mfma_f32_16x16x32_bf16 v[38:41], v[186:189], v[202:205], v[38:41]
	v_mfma_f32_16x16x32_bf16 v[38:41], v[190:193], v[206:209], v[38:41]
	v_mfma_f32_16x16x32_bf16 v[30:33], v[160:163], v[210:213], v[30:33]
	v_mfma_f32_16x16x32_bf16 v[30:33], v[182:185], v[214:217], v[30:33]
	v_mfma_f32_16x16x32_bf16 v[22:25], v[186:189], v[210:213], v[22:25]
	v_mfma_f32_16x16x32_bf16 v[22:25], v[190:193], v[214:217], v[22:25]
	v_mfma_f32_16x16x32_bf16 v[10:13], v[160:163], v[218:221], v[10:13]
	v_mfma_f32_16x16x32_bf16 v[10:13], v[182:185], v[222:225], v[10:13]
	v_mfma_f32_16x16x32_bf16 v[2:5], v[186:189], v[218:221], v[2:5]
	v_mfma_f32_16x16x32_bf16 v[2:5], v[190:193], v[222:225], v[2:5]
	s_setprio 0
	s_barrier
	s_add_i32 s41, 0, 0x18000
	s_add_i32 s42, 0, 0x1c000
	v_add_u32_e32 v156, s41, v171
	v_add_u32_e32 v164, s42, v171
	ds_read_b128 v[134:137], v156
	ds_read_b128 v[148:151], v156 offset:1024
	ds_read_b128 v[152:155], v156 offset:2048
	ds_read_b128 v[156:159], v156 offset:3072
	ds_read_b128 v[160:163], v164
	ds_read_b128 v[182:185], v164 offset:1024
	ds_read_b128 v[186:189], v164 offset:2048
	ds_read_b128 v[190:193], v164 offset:3072
	s_add_u32 s22, s22, 0x40000
	s_addc_u32 s23, s23, 0
	s_mov_b32 m0, s28
	v_lshl_add_u64 v[234:235], s[22:23], 0, v[140:141]
	ds_read_b128 v[194:197], v175 offset:32768
	ds_read_b128 v[198:201], v175 offset:33792
	ds_read_b128 v[202:205], v175 offset:34816
	ds_read_b128 v[206:209], v175 offset:35840
	ds_read_b128 v[210:213], v175 offset:36864
	ds_read_b128 v[214:217], v175 offset:37888
	ds_read_b128 v[218:221], v175 offset:38912
	ds_read_b128 v[222:225], v175 offset:39936
	global_load_lds_dwordx4 v[234:235], off
	v_lshl_add_u64 v[234:235], s[22:23], 0, v[138:139]
	s_mov_b32 m0, s29
	s_nop 0
	global_load_lds_dwordx4 v[234:235], off
	s_waitcnt vmcnt(8)
	s_waitcnt lgkmcnt(0)
	s_barrier
	s_setprio 1
	s_waitcnt lgkmcnt(0)
	v_mfma_f32_16x16x32_bf16 v[130:133], v[134:137], v[194:197], v[130:133]
	v_mfma_f32_16x16x32_bf16 v[130:133], v[148:151], v[198:201], v[130:133]
	v_mfma_f32_16x16x32_bf16 v[122:125], v[152:155], v[194:197], v[122:125]
	v_mfma_f32_16x16x32_bf16 v[122:125], v[156:159], v[198:201], v[122:125]
	v_mfma_f32_16x16x32_bf16 v[114:117], v[134:137], v[202:205], v[114:117]
	v_mfma_f32_16x16x32_bf16 v[114:117], v[148:151], v[206:209], v[114:117]
	v_mfma_f32_16x16x32_bf16 v[106:109], v[152:155], v[202:205], v[106:109]
	v_mfma_f32_16x16x32_bf16 v[106:109], v[156:159], v[206:209], v[106:109]
	v_mfma_f32_16x16x32_bf16 v[98:101], v[134:137], v[210:213], v[98:101]
	v_mfma_f32_16x16x32_bf16 v[98:101], v[148:151], v[214:217], v[98:101]
	v_mfma_f32_16x16x32_bf16 v[90:93], v[152:155], v[210:213], v[90:93]
	v_mfma_f32_16x16x32_bf16 v[90:93], v[156:159], v[214:217], v[90:93]
	v_mfma_f32_16x16x32_bf16 v[82:85], v[134:137], v[218:221], v[82:85]
	v_mfma_f32_16x16x32_bf16 v[82:85], v[148:151], v[222:225], v[82:85]
	v_mfma_f32_16x16x32_bf16 v[74:77], v[152:155], v[218:221], v[74:77]
	v_mfma_f32_16x16x32_bf16 v[74:77], v[156:159], v[222:225], v[74:77]
	s_setprio 0
	s_setprio 1
	v_mfma_f32_16x16x32_bf16 v[126:129], v[160:163], v[194:197], v[126:129]
	v_mfma_f32_16x16x32_bf16 v[126:129], v[182:185], v[198:201], v[126:129]
	v_mfma_f32_16x16x32_bf16 v[118:121], v[186:189], v[194:197], v[118:121]
	v_mfma_f32_16x16x32_bf16 v[118:121], v[190:193], v[198:201], v[118:121]
	v_mfma_f32_16x16x32_bf16 v[110:113], v[160:163], v[202:205], v[110:113]
	v_mfma_f32_16x16x32_bf16 v[110:113], v[182:185], v[206:209], v[110:113]
	v_mfma_f32_16x16x32_bf16 v[102:105], v[186:189], v[202:205], v[102:105]
	v_mfma_f32_16x16x32_bf16 v[102:105], v[190:193], v[206:209], v[102:105]
	v_mfma_f32_16x16x32_bf16 v[94:97], v[160:163], v[210:213], v[94:97]
	v_mfma_f32_16x16x32_bf16 v[94:97], v[182:185], v[214:217], v[94:97]
	v_mfma_f32_16x16x32_bf16 v[86:89], v[186:189], v[210:213], v[86:89]
	v_mfma_f32_16x16x32_bf16 v[86:89], v[190:193], v[214:217], v[86:89]
	v_mfma_f32_16x16x32_bf16 v[78:81], v[160:163], v[218:221], v[78:81]
	v_mfma_f32_16x16x32_bf16 v[78:81], v[182:185], v[222:225], v[78:81]
	v_mfma_f32_16x16x32_bf16 v[70:73], v[186:189], v[218:221], v[70:73]
	v_mfma_f32_16x16x32_bf16 v[70:73], v[190:193], v[222:225], v[70:73]
	s_setprio 0
	s_barrier
	s_add_i32 s22, s41, s13
	v_lshl_add_u64 v[226:227], v[226:227], 0, s[92:93]
	s_mov_b32 m0, s22
	ds_read_b128 v[194:197], v175 offset:49152
	ds_read_b128 v[198:201], v175 offset:50176
	ds_read_b128 v[202:205], v175 offset:51200
	ds_read_b128 v[206:209], v175 offset:52224
	ds_read_b128 v[210:213], v175 offset:53248
	ds_read_b128 v[214:217], v175 offset:54272
	ds_read_b128 v[218:221], v175 offset:55296
	ds_read_b128 v[222:225], v175 offset:56320
	global_load_lds_dwordx4 v[226:227], off
	s_add_i32 m0, s22, 0x2000
	s_add_u32 s20, s20, 0x40080
	v_lshl_add_u64 v[226:227], v[228:229], 0, s[92:93]
	s_addc_u32 s21, s21, 0
	s_add_i32 s22, s42, s13
	global_load_lds_dwordx4 v[226:227], off
	v_lshl_add_u64 v[226:227], s[20:21], 0, v[0:1]
	s_mov_b32 m0, s22
	s_nop 0
	global_load_lds_dwordx4 v[226:227], off
	v_lshl_add_u64 v[226:227], s[20:21], 0, v[14:15]
	s_add_i32 m0, s22, 0x2000
	s_nop 0
	global_load_lds_dwordx4 v[226:227], off
	v_lshl_add_u64 v[226:227], v[230:231], 0, s[92:93]
	s_mov_b32 m0, s30
	s_nop 0
	global_load_lds_dwordx4 v[226:227], off
	v_lshl_add_u64 v[226:227], v[232:233], 0, s[92:93]
	s_mov_b32 m0, s31
	s_nop 0
	global_load_lds_dwordx4 v[226:227], off
	s_waitcnt vmcnt(8)
	s_waitcnt lgkmcnt(0)
	s_barrier
	s_setprio 1
	s_waitcnt lgkmcnt(0)
	v_mfma_f32_16x16x32_bf16 v[66:69], v[134:137], v[194:197], v[66:69]
	v_mfma_f32_16x16x32_bf16 v[66:69], v[148:151], v[198:201], v[66:69]
	v_mfma_f32_16x16x32_bf16 v[58:61], v[152:155], v[194:197], v[58:61]
	v_mfma_f32_16x16x32_bf16 v[58:61], v[156:159], v[198:201], v[58:61]
	v_mfma_f32_16x16x32_bf16 v[50:53], v[134:137], v[202:205], v[50:53]
	v_mfma_f32_16x16x32_bf16 v[50:53], v[148:151], v[206:209], v[50:53]
	v_mfma_f32_16x16x32_bf16 v[42:45], v[152:155], v[202:205], v[42:45]
	v_mfma_f32_16x16x32_bf16 v[42:45], v[156:159], v[206:209], v[42:45]
	v_mfma_f32_16x16x32_bf16 v[34:37], v[134:137], v[210:213], v[34:37]
	v_mfma_f32_16x16x32_bf16 v[34:37], v[148:151], v[214:217], v[34:37]
	v_mfma_f32_16x16x32_bf16 v[26:29], v[152:155], v[210:213], v[26:29]
	v_mfma_f32_16x16x32_bf16 v[26:29], v[156:159], v[214:217], v[26:29]
	v_mfma_f32_16x16x32_bf16 v[18:21], v[134:137], v[218:221], v[18:21]
	v_mfma_f32_16x16x32_bf16 v[18:21], v[148:151], v[222:225], v[18:21]
	v_mfma_f32_16x16x32_bf16 v[6:9], v[152:155], v[218:221], v[6:9]
	v_mfma_f32_16x16x32_bf16 v[6:9], v[156:159], v[222:225], v[6:9]
	s_setprio 0
	s_setprio 1
	v_mfma_f32_16x16x32_bf16 v[62:65], v[160:163], v[194:197], v[62:65]
	v_mfma_f32_16x16x32_bf16 v[62:65], v[182:185], v[198:201], v[62:65]
	v_mfma_f32_16x16x32_bf16 v[54:57], v[186:189], v[194:197], v[54:57]
	v_mfma_f32_16x16x32_bf16 v[54:57], v[190:193], v[198:201], v[54:57]
	v_mfma_f32_16x16x32_bf16 v[46:49], v[160:163], v[202:205], v[46:49]
	v_mfma_f32_16x16x32_bf16 v[46:49], v[182:185], v[206:209], v[46:49]
	v_mfma_f32_16x16x32_bf16 v[38:41], v[186:189], v[202:205], v[38:41]
	v_mfma_f32_16x16x32_bf16 v[38:41], v[190:193], v[206:209], v[38:41]
	v_mfma_f32_16x16x32_bf16 v[30:33], v[160:163], v[210:213], v[30:33]
	v_mfma_f32_16x16x32_bf16 v[30:33], v[182:185], v[214:217], v[30:33]
	v_mfma_f32_16x16x32_bf16 v[22:25], v[186:189], v[210:213], v[22:25]
	v_mfma_f32_16x16x32_bf16 v[22:25], v[190:193], v[214:217], v[22:25]
	v_mfma_f32_16x16x32_bf16 v[10:13], v[160:163], v[218:221], v[10:13]
	v_mfma_f32_16x16x32_bf16 v[10:13], v[182:185], v[222:225], v[10:13]
	v_mfma_f32_16x16x32_bf16 v[2:5], v[186:189], v[218:221], v[2:5]
	v_mfma_f32_16x16x32_bf16 v[2:5], v[190:193], v[222:225], v[2:5]
	s_setprio 0
	s_barrier
	s_add_i32 s40, s40, 2
	s_add_u32 s4, s4, 0x100
	s_addc_u32 s5, s5, 0
	s_add_u32 s38, s38, 0x100
	s_addc_u32 s39, s39, 0
	s_cmp_gt_u32 s40, 13
	s_cbranch_scc0 .LBB0_893
	s_and_b64 vcc, exec, s[8:9]
	s_cbranch_vccz .LBB0_896
	s_barrier
